# P0 load balance: the rope and SSM power tables are computed by workgroups 64-192 (which have 21 transpose tiles) instead of 0-128 (0-63 have 22), shortening the P0 tail
# speedup vs baseline: 1.0021x; 1.0021x over previous
; __global__ void __launch_bounds__(NTHR, 2) fwd_megakernel(Params p) {
;     ...
;         for (long i = gtid; i < LL * 32; i += gthreads) { const int pos = (int)(i >> 5), j = (int)(i & 31); const float invf = 1.0f / powf(10000.0f, (float)(2 * j) / 64.0f); const float ang = (float)pos * invf; COS[i] = cosf(ang); SIN[i] = sinf(ang); }
.LBB0_18:
	s_or_b64 exec, exec, s[0:1]
	s_sub_i32 s98, s2, 64
	s_and_b32 s98, s98, 0xff
	s_mov_b32 s99, 0
	v_lshl_add_u32 v244, s98, 9, v170
	v_mov_b32_e32 v245, 0
	s_mov_b64 s[0:1], 0x10200
	v_cmp_gt_i64_e32 vcc, s[0:1], v[244:245]
	v_lshlrev_b32_e32 v166, 1, v170
	s_and_saveexec_b64 s[14:15], vcc
	s_cbranch_execz .LBB0_29
	s_lshl_b64 s[0:1], s[98:99], 11
	v_mov_b32_e32 v3, 0
	s_add_u32 s0, s92, s0
	v_mov_b32_e32 v147, v3
	s_addc_u32 s1, s93, s1
	v_lshl_add_u64 v[4:5], s[0:1], 0, v[146:147]
	s_mov_b64 s[0:1], 0x6b00000
	s_mov_b32 s38, 0x31739010
	v_lshl_add_u64 v[4:5], v[4:5], 0, s[0:1]
	s_lshl_b64 s[34:35], s[96:97], 11
	v_lshl_add_u32 v1, s98, 10, v166
	s_lshl_b32 s33, s96, 10
	s_mov_b64 s[36:37], 0
	v_mov_b32_e32 v10, 0x461c4000
	v_mov_b32_e32 v11, 0x3e91f4c4
	s_mov_b32 s39, 0xbf2aaaaa
	s_movk_i32 s44, 0x204
	s_mov_b32 s45, 0x7f800000
	s_mov_b32 s46, 0x42b17218
	v_mov_b32_e32 v12, 0x37000000
	v_mov_b32_e32 v13, 0x7f800000
	s_mov_b32 s47, 0xfe5163ab
	s_mov_b32 s48, 0x3c439041
	s_mov_b32 s49, 0xdb629599
	s_mov_b32 s50, 0xf534ddc0
	s_mov_b32 s51, 0xfc2757d1
	s_mov_b32 s52, 0x4e441529
	s_mov_b32 s53, 0xa2f9836e
	s_mov_b32 s54, 0x3fc90fda
	s_mov_b32 s55, 0xbfc90fda
	v_mov_b32_e32 v14, 0x3c0881c4
	v_mov_b32_e32 v15, 0xbab64f3b
	v_mov_b32_e32 v7, 0x3f2aaaaa
	v_not_b32_e32 v16, 63
	v_not_b32_e32 v17, 31
	v_mov_b32_e32 v18, 0x7fc00000
	v_mov_b64_e32 v[8:9], v[244:245]
	s_branch .LBB0_21

; __global__ void __launch_bounds__(NTHR, 2) fwd_megakernel(Params p) {
;     ...
;         for (long idx = gtid; idx < 4096 * 16; idx += gthreads) {
;             const long i = idx >> 4; const int d = (int)(idx & 15); const int g = (int)(i >> 6);
;             const float lr = p.in[4][i], li = p.in[5][i], dt = expf(p.in[6][g]); const float zr = lr * dt, zi = li * dt;
;             const float er = expf(zr); const float lbr = er * cosf(zi), lbi = er * sinf(zi);
;             const float nr = lbr - 1.0f, ni = lbi, den = lr * lr + li * li;
;             const float cr = (nr * lr + ni * li) / den, ci = (ni * lr - nr * li) / den;
;             const float e0 = expf(zr * (float)d), a0 = zi * (float)d; const float pr = e0 * cosf(a0), pi = e0 * sinf(a0);
;             PWC[idx] = make_float2(pr * cr - pi * ci, pr * ci + pi * cr);
;             const float e1 = expf(zr * (float)(d + 1)), a1 = zi * (float)(d + 1);
;             PW1[idx] = make_float2(e1 * cosf(a1), e1 * sinf(a1));
;         }
.LBB0_29:
	s_or_b64 exec, exec, s[14:15]
	s_mov_b64 s[0:1], 0x10000
	v_cmp_gt_i64_e32 vcc, s[0:1], v[244:245]
	v_and_b32_e32 v147, 15, v170
	v_lshlrev_b32_e32 v128, 3, v170
	s_and_saveexec_b64 s[8:9], vcc
	s_cbranch_execz .LBB0_56
	s_lshl_b64 s[0:1], s[98:99], 12
	v_mov_b32_e32 v3, 0
	s_add_u32 s0, s92, s0
	v_mov_b32_e32 v129, v3
	s_addc_u32 s1, s93, s1
	v_add_u32_e32 v2, 1, v147
	v_lshl_add_u64 v[4:5], s[0:1], 0, v[128:129]
	s_mov_b64 s[0:1], 0x6a00000
	v_cvt_f32_ubyte0_e32 v12, v2
	v_lshl_add_u64 v[4:5], v[4:5], 0, s[0:1]
	s_lshl_b64 s[0:1], s[98:99], 31
	v_lshlrev_b32_e32 v2, 22, v170
	v_cvt_f32_ubyte0_e32 v1, v147
	s_lshl_b64 s[14:15], s[96:97], 12
	v_lshl_add_u64 v[6:7], s[0:1], 0, v[2:3]
	s_lshl_b64 s[34:35], s[96:97], 31
	s_mov_b64 s[36:37], 0
	s_mov_b32 s33, 0x3fb8aa3b
	s_mov_b32 s44, 0xc2ce8ed0
	s_mov_b32 s45, 0x42b17218
	v_mov_b32_e32 v13, 0x7f800000
	s_brev_b32 s46, 18
	s_mov_b32 s47, 0xfe5163ab
	s_mov_b32 s48, 0x3c439041
	s_mov_b32 s49, 0xdb629599
	s_mov_b32 s50, 0xf534ddc0
	s_mov_b32 s51, 0xfc2757d1
	s_mov_b32 s52, 0x4e441529
	s_mov_b32 s53, 0xa2f9836e
	s_mov_b32 s54, 0x3fc90fda
	s_mov_b32 s55, 0x3f22f983
	s_mov_b32 s56, 0xbfc90fda
	v_mov_b32_e32 v14, 0x3c0881c4
	v_mov_b32_e32 v15, 0xbab64f3b
	s_brev_b32 s57, 1
	s_movk_i32 s58, 0x1f8
	v_not_b32_e32 v16, 63
	v_not_b32_e32 v17, 31
	v_mov_b32_e32 v18, 0x7fc00000
	v_mov_b64_e32 v[8:9], v[244:245]
	s_branch .LBB0_32
